# FN 8,13,16: additionally the L0 down-projection phase applies layer 1's first norm to the latent rows in its epilogue; the following norm phase only handles the context rows (split-K partial sums)
# baseline (speedup 1.0000x reference)
; #define GAS __attribute__((address_space(1)))
; template <class T> __device__ __forceinline__ GAS T* gptr(T* q) { return (GAS T*)(unsigned long long)uptr(q); }
; __device__ __forceinline__ void gemm_epilogue(LAS unsigned char* lds, const GD& gd, const f32x4 (&acc)[2][2][4][2], const Unit& u) {
;     ...
;     if (mode == M_RES) {
;         const bool lat = row_u < NL;
;         const int rb = lat ? (row_u >> 12) : 4;
;         GAS const float* gmr = gptr(gd.gm + rb * 6144 + u.pn * BM);
;         GAS const float* xin = gptr((lat ? gd.xin_lat : gd.xin_ctx - (size_t)NL * DM) + (size_t)row_u * DM + u.pn * BM);
;         GAS float* xout = gptr((lat ? gd.xout_lat : gd.xout_ctx - (size_t)NL * DM) + (size_t)row_u * DM + u.pn * BM);
.Lmy_fn_c2:
	s_cmp_lg_u32 s17, 8
	s_cbranch_scc1 .Lmy_fn_c4
	s_cmp_lg_u32 s2, 0
	s_cbranch_scc1 .Lmy_fn_c4
	s_mov_b32 s92, 1
	s_movk_i32 s93, 4
	s_mov_b32 s94, 122880
	s_movk_i32 s95, 4096
	s_movk_i32 s32, 0
	s_branch .Lmy_fn_go

; __device__ __forceinline__ int otid() { int t = threadIdx.x; asm volatile("" : "+v"(t)); return t; }
; #define GAS __attribute__((address_space(1)))
; __device__ void phase_norm(const Params& p, int l, int which) {
;     const int tid = otid(), lane = tid & 63, gw = blockIdx.x * 8 + (tid >> 6), nw = gridDim.x * 8;
;     const int nrows = (l == 1 && which == 1) ? NL : NR;
;     const bool first = (l == 0 && which == 0);
;     GAS const f32x4* gn = (GAS const f32x4*)(unsigned long long)((which ? p.norm_ffn : p.norm_mix) + l * 1024);
;     GAS const float* mod = (GAS const float*)(unsigned long long)(p.ws + OFF_MOD) + (size_t)l * 5 * 6144 + (which ? 3072 : 0);
;     GAS bf16_t* H = (GAS bf16_t*)(unsigned long long)(p.ws + OFF_H);
;     for (int row = gw; row < nrows; row += nw) {
;         GAS const f32x4* xr; int rb;
;         if (row < NL) { xr = (GAS const f32x4*)(unsigned long long)((first ? p.x : p.out) + (size_t)row * DM); rb = row >> 12; }
;         else { xr = (GAS const f32x4*)(unsigned long long)((first ? p.ctx : (const float*)(p.ws + OFF_XC)) + (size_t)(row - NL) * DM); rb = 4; }
.LBB0_631:
	s_andn2_b64 vcc, exec, s[0:1]
	s_cbranch_vccnz .LBB0_643
	s_cmp_eq_u32 s17, 5
	v_readlane_b32 s0, v255, 5
	s_cselect_b64 vcc, -1, 0
	s_cmp_lt_u32 s0, 8
	s_cselect_b64 s[4:5], -1, 0
	s_and_b64 s[0:1], s[4:5], vcc
	s_and_b64 s[0:1], s[0:1], exec
	s_movk_i32 s0, 0x4400
	s_cselect_b32 s8, 0x4000, s0
	v_readlane_b32 s0, v254, 37
	v_mov_b32_e32 v12, v210
	s_nop 0
	v_mov_b32_e32 v0, s0
	v_readlane_b32 s0, v254, 38
	s_nop 1
	v_mov_b32_e32 v1, s0
	v_readlane_b32 s0, v254, 40
	ds_read_b64 v[8:9], v0
	ds_read_b64 v[10:11], v1
	v_mov_b32_e32 v0, s0
	v_readlane_b32 s0, v254, 36
	s_nop 1
	v_mov_b32_e32 v1, s0
	ds_read_b128 v[4:7], v0
	ds_read_b128 v[0:3], v1
	v_readlane_b32 s0, v253, 5
	v_ashrrev_i32_e32 v13, 6, v12
	s_nop 0
	v_add_u32_e32 v64, s0, v13
	s_cmp_lg_u32 s16, 9
	s_cbranch_scc1 .Lmy_fn_nr
	s_cmpk_lg_u32 s72, 0x100
	s_cbranch_scc1 .Lmy_fn_nr
	v_add_u32_e32 v64, 0x4000, v64
.Lmy_fn_nr:
	v_cmp_gt_i32_e64 s[40:41], s8, v64
	s_and_saveexec_b64 s[0:1], s[40:41]
	s_cbranch_execz .LBB0_642
	s_and_b64 s[6:7], vcc, exec
	s_cselect_b32 s2, 0x3000, 0
	s_waitcnt lgkmcnt(0)
	v_lshl_add_u64 v[14:15], v[2:3], 0, s[54:55]
	v_lshl_add_u64 v[66:67], v[14:15], 0, s[2:3]
	v_readlane_b32 s2, v255, 0
	s_lshl_b32 s10, s2, 10
	v_cndmask_b32_e64 v13, 0, 1, vcc
	s_ashr_i32 s11, s10, 31
	v_and_b32_e32 v12, 63, v12
	v_or_b32_e32 v13, s2, v13
	s_lshl_b64 s[10:11], s[10:11], 2
	v_cndmask_b32_e32 v5, v5, v7, vcc
	v_cndmask_b32_e32 v4, v4, v6, vcc
	s_xor_b64 s[6:7], vcc, -1
	v_lshl_add_u64 v[4:5], v[4:5], 0, s[10:11]
	s_mov_b64 s[10:11], 0x200000
	v_lshlrev_b32_e32 v68, 4, v12
	v_mov_b32_e32 v69, v97
	v_cmp_eq_u32_e32 vcc, 0, v13
	v_lshlrev_b32_e32 v96, 3, v12
	v_lshl_add_u64 v[6:7], v[2:3], 0, s[10:11]
	v_lshl_add_u64 v[70:71], v[4:5], 0, v[68:69]
	v_or_b32_e32 v4, 64, v12
	v_or_b32_e32 v14, 0x80, v12
	v_or_b32_e32 v16, 0xc0, v12
	v_cndmask_b32_e32 v75, v1, v9, vcc
	v_cndmask_b32_e32 v74, v0, v8, vcc
	s_mov_b64 s[10:11], 0xc600000
	s_and_b64 s[18:19], s[6:7], s[4:5]
	v_lshl_add_u64 v[0:1], v[2:3], 0, v[96:97]
	s_mov_b64 s[4:5], 0x4100000
	v_cndmask_b32_e32 v73, v7, v11, vcc
	v_cndmask_b32_e32 v72, v6, v10, vcc
	v_lshl_add_u64 v[76:77], v[2:3], 0, s[10:11]
	v_lshl_add_u64 v[78:79], v[0:1], 0, s[4:5]
	s_mov_b64 s[20:21], 0
	v_lshlrev_b32_e32 v96, 4, v12
	v_lshlrev_b32_e32 v80, 4, v4
	v_lshlrev_b32_e32 v82, 4, v14
	v_lshlrev_b32_e32 v84, 4, v16
	s_branch .LBB0_635
